# variant: scan / A pass 2 order swapped per workgroup (bit 3 clear) instead of per wave half
# baseline (speedup 1.0000x reference)
; #define LAS __attribute__((address_space(3)))
; #define LAUNDER() int tp = TID0(); const int tid = tp, lane = tp & 63, wave = __builtin_amdgcn_readfirstlane(tp >> 6); (void)tid; (void)lane; (void)wave
; __global__ void __launch_bounds__(512) fwd_kernel(Args a) {
;     ...
;         if (IN(pb + 3) && EN_SCAN) { LAUNDER(); ssd_scan(STATES, TOT, blockIdx.x * 512 + tid, G * 512); }
;         if (IN(pb + 3) && EN_A) { LAUNDER(); LAS char* vt = (LAS char*)lds + wave * 16384;
;             for (int u = blockIdx.x; u < 512; u += G) { mixerA2_unit(u, PROJ, YC, LPA, KMAX + l * 1024, vt, wave, lane); } }
.Lsw_scan:
	s_cmp_eq_u32 s100, 0
	s_cbranch_scc0 .Lsw_doscan
	s_bitcmp1_b32 s66, 3
	s_cbranch_scc1 .Lsw_doscan
	s_mov_b32 s100, 1
	s_branch .Lsw_a2
